# SA-read-next-step-page-table-entry-one-step-ahead
# baseline (speedup 1.0000x reference)
; template <int MODE> __device__ __forceinline__ void item(const void* const* in, const bf16* QABS, const unsigned char* W8, const bf16* ROPEB, float* PO, float* PL, float sref, int b, int half, LAS unsigned char* lds, int tid_, int wave, int lane_) {
;     ...
;     for (int hp = 0; hp < NHP; ++hp) { SA_IDS();
;         const int par = hp & 1;
;         LAS unsigned char* cs = lds + OFF_CS + par * CSB; LAS unsigned char* c8 = lds + OFF_C8 + par * C8B;
;         LAS unsigned char* csn = lds + OFF_CS + (par ^ 1) * CSB; LAS unsigned char* c8n = lds + OFF_C8 + (par ^ 1) * C8B;
;         const int kssr = OFF_KSS + par * 256, kssw = OFF_KSS + (par ^ 1) * 256;
;         const bool more = hp + 2 < NHP; const int hn = more ? hp + 2 : hp; SA_SRC(hn);
;         asm volatile("s_waitcnt vmcnt(0)" ::: "memory");
;         asm volatile("" : "+v"(va[0]), "+v"(va[1]), "+v"(va[2]), "+v"(va[3]), "+v"(vb[0]), "+v"(vb[1]), "+v"(vb[2]), "+v"(vb[3]));
;         asm volatile("" : "+v"(x1), "+v"(x2), "+v"(cw), "+v"(sw));
;         { f32x16 t0 = {}, t1 = {}, t2 = {}, t3 = {}; v8i cfa, cfb;
;           SA_R(cfa, 0, 0); SA_R(cfb, 0, 1); SA_SB();
;           SA_SEG(t0, t1, 0, 0, (void)0, SA_R(cfa, 0, 2), SA_R(cfb, 0, 3)); if (more) SA_LD(0); SA_SB();
;           SA_SEG(t0, t1, 2, 1, (void)0, SA_R(cfa, 1, 0), SA_R(cfb, 1, 1)); if (more) SA_LD(1); SA_SB();
;           if (tid < 256) SA_AKR(csn, kssw);
;           SA_SB(); if (more) SA_LDK(hn); SA_SB();
;           SA_SEG(t2, t3, 0, 2, SA_BRED(t0, t1, 0, kssr); SA_SB(), SA_R(cfa, 1, 2), SA_R(cfb, 1, 3)); if (more) SA_LD(2); SA_SB();
;           SA_SEG(t2, t3, 2, 3, (void)0, (void)0, (void)0); if (more) SA_LD(3); SA_SB();
;           SA_BRED(t2, t3, 1, kssr); }
;         SA_BAR();
;         { f32x4 p4 = {0.f, 0.f, 0.f, 0.f}, p5 = {0.f, 0.f, 0.f, 0.f}; const int key = 16 * kq + (lq & 15);
;           bf16x8 cf[9], qf[9];
;           { LAS unsigned char* cb = cs + quad * CHS + key * 16; LAS unsigned char* qb = lds + OFF_QA + quad * 512 + cs_col * 16;
; #pragma unroll
;             for (int s2 = 0; s2 < 9; ++s2) { cf[s2] = *(const LAS bf16x8*)(cb + s2 * 4 * CHS); qf[s2] = *(const LAS bf16x8*)(qb + s2 * 2048); } }
; #pragma unroll
;           for (int s2 = 0; s2 < 9; ++s2) { if (s2 & 1) p5 = __builtin_amdgcn_mfma_f32_16x16x32_bf16(cf[s2], qf[s2], p5, 0, 0, 0); else p4 = __builtin_amdgcn_mfma_f32_16x16x32_bf16(cf[s2], qf[s2], p4, 0, 0, 0); }
.LBB0_1363:
	v_mov_b32_e32 v229, 0x20c84
	ds_read_b32 v229, v229
	s_waitcnt lgkmcnt(0)
	s_barrier
	v_mov_b32_e32 v189, 0
	s_mov_b32 s65, 0
	v_mov_b32_e32 v2, 0
	v_mov_b32_e32 v3, v189
	v_mov_b32_e32 v4, v189
	v_mov_b32_e32 v5, v189
	v_mov_b32_e32 v6, v189
	v_mov_b32_e32 v7, v189
	v_mov_b32_e32 v8, v189
	v_mov_b32_e32 v9, v189
	v_mov_b32_e32 v10, v189
	v_mov_b32_e32 v11, v189
	v_mov_b32_e32 v12, v189
	v_mov_b32_e32 v13, v189
	v_mov_b32_e32 v14, v189
	v_mov_b32_e32 v15, v189
	v_mov_b32_e32 v16, v189
	v_mov_b32_e32 v17, v189
	s_branch .LBB0_1365
.LBB0_1364:
	s_or_b64 exec, exec, s[4:5]
	v_cvt_pk_bf16_f32 v22, v22, v24
	v_mov_b32_e32 v24, s0
	s_movk_i32 s4, 0x90
	v_mad_u32_u24 v20, v20, s4, v24
	v_lshlrev_b32_e32 v21, 3, v21
	v_add3_u32 v20, v20, v21, s92
	v_cvt_pk_bf16_f32 v23, v23, v25
	ds_write_b64 v20, v[22:23]
	v_and_b32_e32 v20, 16, v205
	v_and_b32_e32 v21, 8, v207
	v_or3_b32 v20, v20, v21, s36
	v_lshrrev_b32_e32 v20, 3, v20
	v_mul_lo_u32 v20, v20, s8
	v_lshlrev_b32_e32 v21, 7, v204
	v_lshlrev_b32_e32 v19, 2, v19
	v_and_b32_e32 v19, 48, v19
	v_add3_u32 v20, s6, v20, v21
	s_waitcnt lgkmcnt(0)
	s_barrier
	s_add_i32 s98, s65, 1
	s_add_i32 s99, s98, 2
	s_cmp_lt_u32 s98, 62
	s_cselect_b32 s98, s99, s98
	s_lshr_b32 s98, s98, 1
	s_lshl_b32 s98, s98, 2
	s_add_i32 s98, s98, 0x20c80
	v_mov_b32_e32 v229, s98
	ds_read_b32 v229, v229
	v_add3_u32 v19, v20, v19, v208
	v_mul_u32_u24_e32 v24, 0x90, v203
	v_lshlrev_b32_e32 v25, 4, v204
	ds_read_b64_tr_b16 v[20:21], v19
	ds_read_b64_tr_b16 v[22:23], v19 offset:64
	v_add3_u32 v32, s0, v24, v25
	ds_read_b128 v[24:27], v32
	ds_read_b64_tr_b16 v[28:29], v19 offset:256
	s_waitcnt lgkmcnt(1)
	v_mfma_f32_32x32x16_bf16 v[2:17], v[20:23], v[24:27], v[2:17]
	ds_read_b64_tr_b16 v[30:31], v19 offset:320
	ds_read_b128 v[20:23], v32 offset:32
	ds_read_b64_tr_b16 v[24:25], v19 offset:512
	ds_read_b64_tr_b16 v[26:27], v19 offset:576
	s_add_i32 s4, 0, 0x20a80
	v_add_u32_e32 v18, s4, v18
	v_add_u32_e32 v33, s4, v186
	s_add_i32 s65, s65, 1
	s_cmp_eq_u32 s65, 64
	s_waitcnt lgkmcnt(2)
	v_mfma_f32_32x32x16_bf16 v[2:17], v[28:31], v[20:23], v[2:17]
	ds_read_b128 v[20:23], v32 offset:64
	ds_read_b64_tr_b16 v[28:29], v19 offset:768
	ds_read_b64_tr_b16 v[30:31], v19 offset:832
	s_waitcnt lgkmcnt(2)
	v_mfma_f32_32x32x16_bf16 v[2:17], v[24:27], v[20:23], v[2:17]
	ds_read_b32 v22, v18
	ds_read2st64_b32 v[24:25], v33 offset1:1
	ds_read_b32 v23, v33 offset:384
	ds_read_b128 v[18:21], v32 offset:96
	s_waitcnt lgkmcnt(0)
	s_barrier
	s_waitcnt lgkmcnt(1)
	v_pk_add_f32 v[22:23], v[24:25], v[22:23]
	s_nop 0
	v_add_f32_e32 v22, v22, v23
	s_waitcnt lgkmcnt(0)
	v_mfma_f32_32x32x16_bf16 v[2:17], v[28:31], v[18:21], v[2:17]
	v_add_f32_e32 v189, v189, v22
	s_cbranch_scc1 .LBB0_1384
.LBB0_1365:
	s_and_b32 s95, s65, 1
	s_mul_i32 s4, s95, 0x4100
	s_xor_b32 s96, s95, 1
	s_add_i32 s5, s9, s4
	s_mul_i32 s4, s96, 0x9240
	s_add_i32 s18, s4, 0
	s_mul_i32 s4, s96, 0x4100
	s_add_i32 s4, s9, s4
	s_add_i32 s10, s65, 2
	s_cmp_lt_u32 s65, 62
	s_cselect_b64 s[6:7], -1, 0
	s_and_b64 s[16:17], s[6:7], exec
	s_cselect_b32 s19, s10, s65
	s_lshr_b32 s10, s19, 1
	s_lshl_b32 s16, s10, 2
	s_add_i32 s16, s16, 0
	s_add_i32 s16, s16, 0x20c80
	v_mov_b32_e32 v205, v188
	v_and_b32_e32 v203, 31, v205
	v_bfe_u32 v204, v205, 5, 1
	s_lshl_b32 s19, s19, 6
	v_lshlrev_b32_e32 v214, 5, v203
	s_waitcnt lgkmcnt(0)
	v_readfirstlane_b32 s16, v229
	v_mov_b32_e32 v18, s5
	s_ashr_i32 s17, s16, 31
	v_mad_u32_u24 v130, v204, s33, v18
	s_lshl_b64 s[16:17], s[16:17], 7
	s_and_b32 s22, s19, 64
	v_add_u32_e32 v131, v130, v214
	s_or_b32 s16, s16, s22
	s_waitcnt vmcnt(0)
	ds_read_b128 v[34:37], v131
	ds_read_b128 v[38:41], v131 offset:16
	ds_read_b128 v[50:53], v131 offset:4160
	ds_read_b128 v[54:57], v131 offset:4176
	s_add_u32 s24, s16, s20
	s_addc_u32 s25, s17, s21
	v_readlane_b32 s40, v254, 15
	s_lshl_b64 s[24:25], s[24:25], 10
	v_readlane_b32 s48, v254, 23
	v_and_b32_e32 v206, 63, v205
	v_readlane_b32 s49, v254, 24
	s_add_u32 s24, s48, s24
	s_addc_u32 s25, s49, s25
	v_lshlrev_b32_e32 v186, 4, v206
	v_lshlrev_b32_e32 v207, 2, v205
	v_lshl_add_u64 v[194:195], s[24:25], 0, v[186:187]
	v_readlane_b32 s41, v254, 16
	v_readlane_b32 s42, v254, 17
	v_readlane_b32 s43, v254, 18
	v_readlane_b32 s44, v254, 19
	v_readlane_b32 s45, v254, 20
	v_readlane_b32 s46, v254, 21
	v_readlane_b32 s47, v254, 22
	v_readlane_b32 s50, v254, 25
	v_readlane_b32 s51, v254, 26
	v_readlane_b32 s52, v254, 27
	v_readlane_b32 s53, v254, 28
	v_readlane_b32 s54, v254, 29
	v_readlane_b32 s55, v254, 30
	s_cmp_gt_u32 s65, 61
	s_waitcnt lgkmcnt(2)
	v_mfma_scale_f32_32x32x64_f8f6f4 v[18:33], v[66:73], v[34:41], 0, v199, v199 op_sel_hi:[0,0,0]
	v_bfe_u32 v44, v205, 1, 5
	v_and_b32_e32 v58, 1, v205
	v_mov_b32_e32 v45, s18
	v_mad_u32_u24 v209, v44, s8, v45
	v_lshlrev_b32_e32 v208, 3, v58
	v_add3_u32 v44, v209, s36, v208
	v_cvt_pk_bf16_f32 v42, v154, v155
	v_cvt_pk_bf16_f32 v43, v156, v157
	ds_write_b64 v44, v[42:43]
	v_mfma_scale_f32_32x32x64_f8f6f4 v[34:49], v[74:81], v[34:41], 0, v199, v199 op_sel_hi:[0,0,0]
	v_mov_b32_e32 v59, v187
	v_cvt_pk_fp8_f32 v59, v154, v155
	v_bfe_u32 v60, v205, 3, 3
	v_mov_b32_e32 v61, s4
	v_mad_u32_u24 v210, v60, s33, v61
	v_cvt_pk_fp8_f32 v59, v156, v157 op_sel:[0,0,1]
	v_add_u32_e32 v60, s34, v210
	v_and_b32_e32 v211, 24, v207
	v_lshlrev_b32_e32 v212, 2, v58
	v_add3_u32 v58, v60, v211, v212
	ds_write_b32 v58, v59
	ds_read_b128 v[58:61], v131 offset:8320
	ds_read_b128 v[62:65], v131 offset:8336
	s_waitcnt lgkmcnt(4)
	v_mfma_scale_f32_32x32x64_f8f6f4 v[18:33], v[82:89], v[50:57], v[18:33], v199, v199 op_sel_hi:[0,0,0]
	v_add3_u32 v134, v209, s66, v208
	v_cvt_pk_bf16_f32 v132, v158, v159
	v_cvt_pk_bf16_f32 v133, v160, v161
	ds_write_b64 v134, v[132:133]
	v_mfma_scale_f32_32x32x64_f8f6f4 v[34:49], v[90:97], v[50:57], v[34:49], v199, v199 op_sel_hi:[0,0,0]
	v_mov_b32_e32 v50, v187
	v_cvt_pk_fp8_f32 v50, v158, v159
	v_add_u32_e32 v51, s67, v210
	v_add3_u32 v51, v51, v211, v212
	v_cvt_pk_fp8_f32 v50, v160, v161 op_sel:[0,0,1]
	ds_write_b32 v51, v50
	ds_read_b128 v[50:53], v131 offset:12480
	ds_read_b128 v[54:57], v131 offset:12496
	s_cbranch_scc1 .LBB0_1367
	global_load_dwordx4 v[154:157], v[194:195], off
	v_lshl_add_u64 v[132:133], v[194:195], 0, s[38:39]
	global_load_dwordx4 v[158:161], v[132:133], off

; template <int MODE> __device__ __forceinline__ void item(const void* const* in, const bf16* QABS, const unsigned char* W8, const bf16* ROPEB, float* PO, float* PL, float sref, int b, int half, LAS unsigned char* lds, int tid_, int wave, int lane_) {
;     ...
;     for (int hp = 0; hp < NHP; ++hp) { SA_IDS();
;         const int par = hp & 1;
;         LAS unsigned char* cs = lds + OFF_CS + par * CSB; LAS unsigned char* c8 = lds + OFF_C8 + par * C8B;
;         LAS unsigned char* csn = lds + OFF_CS + (par ^ 1) * CSB; LAS unsigned char* c8n = lds + OFF_C8 + (par ^ 1) * C8B;
;         const int kssr = OFF_KSS + par * 256, kssw = OFF_KSS + (par ^ 1) * 256;
;         const bool more = hp + 2 < NHP; const int hn = more ? hp + 2 : hp; SA_SRC(hn);
;         asm volatile("s_waitcnt vmcnt(0)" ::: "memory");
;         asm volatile("" : "+v"(va[0]), "+v"(va[1]), "+v"(va[2]), "+v"(va[3]), "+v"(vb[0]), "+v"(vb[1]), "+v"(vb[2]), "+v"(vb[3]));
;         asm volatile("" : "+v"(x1), "+v"(x2), "+v"(cw), "+v"(sw));
;         { f32x16 t0 = {}, t1 = {}, t2 = {}, t3 = {}; v8i cfa, cfb;
;           SA_R(cfa, 0, 0); SA_R(cfb, 0, 1); SA_SB();
;           SA_SEG(t0, t1, 0, 0, (void)0, SA_R(cfa, 0, 2), SA_R(cfb, 0, 3)); if (more) SA_LD(0); SA_SB();
;           SA_SEG(t0, t1, 2, 1, (void)0, SA_R(cfa, 1, 0), SA_R(cfb, 1, 1)); if (more) SA_LD(1); SA_SB();
;           if (tid < 256) SA_AKR(csn, kssw);
;           SA_SB(); if (more) SA_LDK(hn); SA_SB();
;           SA_SEG(t2, t3, 0, 2, SA_BRED(t0, t1, 0, kssr); SA_SB(), SA_R(cfa, 1, 2), SA_R(cfb, 1, 3)); if (more) SA_LD(2); SA_SB();
;           SA_SEG(t2, t3, 2, 3, (void)0, (void)0, (void)0); if (more) SA_LD(3); SA_SB();
;           SA_BRED(t2, t3, 1, kssr); }
;         SA_BAR();
;         { f32x4 p4 = {0.f, 0.f, 0.f, 0.f}, p5 = {0.f, 0.f, 0.f, 0.f}; const int key = 16 * kq + (lq & 15);
;           bf16x8 cf[9], qf[9];
;           { LAS unsigned char* cb = cs + quad * CHS + key * 16; LAS unsigned char* qb = lds + OFF_QA + quad * 512 + cs_col * 16;
; #pragma unroll
;             for (int s2 = 0; s2 < 9; ++s2) { cf[s2] = *(const LAS bf16x8*)(cb + s2 * 4 * CHS); qf[s2] = *(const LAS bf16x8*)(qb + s2 * 2048); } }
; #pragma unroll
;           for (int s2 = 0; s2 < 9; ++s2) { if (s2 & 1) p5 = __builtin_amdgcn_mfma_f32_16x16x32_bf16(cf[s2], qf[s2], p5, 0, 0, 0); else p4 = __builtin_amdgcn_mfma_f32_16x16x32_bf16(cf[s2], qf[s2], p4, 0, 0, 0); }
.LBB0_1465:
	v_mov_b32_e32 v229, 0x20c84
	ds_read_b32 v229, v229
	s_waitcnt lgkmcnt(0)
	s_barrier
	v_mov_b32_e32 v189, 0
	s_mov_b32 s97, 0
	v_mov_b32_e32 v2, 0
	v_mov_b32_e32 v3, v189
	v_mov_b32_e32 v4, v189
	v_mov_b32_e32 v5, v189
	v_mov_b32_e32 v6, v189
	v_mov_b32_e32 v7, v189
	v_mov_b32_e32 v8, v189
	v_mov_b32_e32 v9, v189
	v_mov_b32_e32 v10, v189
	v_mov_b32_e32 v11, v189
	v_mov_b32_e32 v12, v189
	v_mov_b32_e32 v13, v189
	v_mov_b32_e32 v14, v189
	v_mov_b32_e32 v15, v189
	v_mov_b32_e32 v16, v189
	v_mov_b32_e32 v17, v189
	s_branch .LBB0_1467
.LBB0_1466:
	s_or_b64 exec, exec, s[4:5]
	v_cvt_pk_bf16_f32 v22, v22, v24
	v_mov_b32_e32 v24, s96
	s_movk_i32 s4, 0x90
	v_mad_u32_u24 v20, v20, s4, v24
	v_lshlrev_b32_e32 v21, 3, v21
	v_add3_u32 v20, v20, v21, s87
	v_cvt_pk_bf16_f32 v23, v23, v25
	ds_write_b64 v20, v[22:23]
	v_and_b32_e32 v20, 16, v204
	v_and_b32_e32 v21, 8, v206
	v_or3_b32 v20, v20, v21, s28
	v_lshrrev_b32_e32 v20, 3, v20
	v_mul_lo_u32 v20, v20, s93
	v_lshlrev_b32_e32 v21, 7, v203
	v_lshlrev_b32_e32 v19, 2, v19
	v_and_b32_e32 v19, 48, v19
	v_add3_u32 v20, s6, v20, v21
	s_waitcnt lgkmcnt(0)
	s_barrier
	s_add_i32 s98, s97, 1
	s_add_i32 s99, s98, 2
	s_cmp_lt_u32 s98, 62
	s_cselect_b32 s98, s99, s98
	s_lshr_b32 s98, s98, 1
	s_lshl_b32 s98, s98, 2
	s_add_i32 s98, s98, 0x20c80
	v_mov_b32_e32 v229, s98
	ds_read_b32 v229, v229
	v_add3_u32 v19, v20, v19, v207
	v_mul_u32_u24_e32 v24, 0x90, v202
	v_lshlrev_b32_e32 v25, 4, v203
	ds_read_b64_tr_b16 v[20:21], v19
	ds_read_b64_tr_b16 v[22:23], v19 offset:64
	v_add3_u32 v32, s96, v24, v25
	ds_read_b128 v[24:27], v32
	ds_read_b64_tr_b16 v[28:29], v19 offset:256
	s_waitcnt lgkmcnt(1)
	v_mfma_f32_32x32x16_bf16 v[2:17], v[20:23], v[24:27], v[2:17]
	ds_read_b64_tr_b16 v[30:31], v19 offset:320
	ds_read_b128 v[20:23], v32 offset:32
	ds_read_b64_tr_b16 v[24:25], v19 offset:512
	ds_read_b64_tr_b16 v[26:27], v19 offset:576
	s_add_i32 s4, 0, 0x20a80
	v_add_u32_e32 v18, s4, v18
	v_add_u32_e32 v33, s4, v186
	s_add_i32 s97, s97, 1
	s_cmp_eq_u32 s97, 64
	s_waitcnt lgkmcnt(2)
	v_mfma_f32_32x32x16_bf16 v[2:17], v[28:31], v[20:23], v[2:17]
	ds_read_b128 v[20:23], v32 offset:64
	ds_read_b64_tr_b16 v[28:29], v19 offset:768
	ds_read_b64_tr_b16 v[30:31], v19 offset:832
	s_waitcnt lgkmcnt(2)
	v_mfma_f32_32x32x16_bf16 v[2:17], v[24:27], v[20:23], v[2:17]
	ds_read_b32 v22, v18
	ds_read2st64_b32 v[24:25], v33 offset1:1
	ds_read_b32 v23, v33 offset:384
	ds_read_b128 v[18:21], v32 offset:96
	s_waitcnt lgkmcnt(0)
	s_barrier
	s_waitcnt lgkmcnt(1)
	v_pk_add_f32 v[22:23], v[24:25], v[22:23]
	s_nop 0
	v_add_f32_e32 v22, v22, v23
	s_waitcnt lgkmcnt(0)
	v_mfma_f32_32x32x16_bf16 v[2:17], v[28:31], v[18:21], v[2:17]
	v_add_f32_e32 v189, v189, v22
	s_cbranch_scc1 .LBB0_1486
.LBB0_1467:
	s_and_b32 s90, s97, 1
	s_mul_i32 s4, s90, 0x4100
	s_xor_b32 s91, s90, 1
	s_add_i32 s5, s94, s4
	s_mul_i32 s4, s91, 0x9240
	s_add_i32 s12, s4, 0
	s_mul_i32 s4, s91, 0x4100
	s_add_i32 s4, s94, s4
	s_add_i32 s13, s97, 2
	s_cmp_lt_u32 s97, 62
	s_cselect_b64 s[6:7], -1, 0
	s_and_b64 s[16:17], s[6:7], exec
	s_cselect_b32 s13, s13, s97
	s_lshr_b32 s22, s13, 1
	s_lshl_b32 s16, s22, 2
	s_add_i32 s16, s16, 0
	s_add_i32 s16, s16, 0x20c80
	v_mov_b32_e32 v204, v188
	v_and_b32_e32 v202, 31, v204
	v_bfe_u32 v203, v204, 5, 1
	s_lshl_b32 s13, s13, 6
	v_lshlrev_b32_e32 v213, 5, v202
	s_waitcnt lgkmcnt(0)
	v_readfirstlane_b32 s16, v229
	v_mov_b32_e32 v18, s5
	s_ashr_i32 s17, s16, 31
	v_mad_u32_u24 v130, v203, s95, v18
	s_lshl_b64 s[16:17], s[16:17], 7
	s_and_b32 s30, s13, 64
	v_add_u32_e32 v131, v130, v213
	s_or_b32 s16, s16, s30
	s_waitcnt vmcnt(0)
	ds_read_b128 v[34:37], v131
	ds_read_b128 v[38:41], v131 offset:16
	ds_read_b128 v[50:53], v131 offset:4160
	ds_read_b128 v[54:57], v131 offset:4176
	s_add_u32 s24, s16, s14
	s_addc_u32 s25, s17, s15
	v_readlane_b32 s36, v254, 15
	s_lshl_b64 s[24:25], s[24:25], 10
	v_readlane_b32 s44, v254, 23
	v_and_b32_e32 v205, 63, v204
	v_readlane_b32 s45, v254, 24
	s_add_u32 s24, s44, s24
	s_addc_u32 s25, s45, s25
	v_lshlrev_b32_e32 v186, 4, v205
	v_lshlrev_b32_e32 v206, 2, v204
	v_lshl_add_u64 v[194:195], s[24:25], 0, v[186:187]
	v_readlane_b32 s37, v254, 16
	v_readlane_b32 s38, v254, 17
	v_readlane_b32 s39, v254, 18
	v_readlane_b32 s40, v254, 19
	v_readlane_b32 s41, v254, 20
	v_readlane_b32 s42, v254, 21
	v_readlane_b32 s43, v254, 22
	v_readlane_b32 s46, v254, 25
	v_readlane_b32 s47, v254, 26
	v_readlane_b32 s48, v254, 27
	v_readlane_b32 s49, v254, 28
	v_readlane_b32 s50, v254, 29
	v_readlane_b32 s51, v254, 30
	s_cmp_gt_u32 s97, 61
	s_waitcnt lgkmcnt(2)
	v_mfma_scale_f32_32x32x64_f8f6f4 v[18:33], v[66:73], v[34:41], 0, v198, v198 op_sel_hi:[0,0,0]
	v_bfe_u32 v44, v204, 1, 5
	v_and_b32_e32 v58, 1, v204
	v_mov_b32_e32 v45, s12
	v_mad_u32_u24 v208, v44, s93, v45
	v_lshlrev_b32_e32 v207, 3, v58
	v_add3_u32 v44, v208, s28, v207
	v_cvt_pk_bf16_f32 v42, v154, v155
	v_cvt_pk_bf16_f32 v43, v156, v157
	ds_write_b64 v44, v[42:43]
	v_mfma_scale_f32_32x32x64_f8f6f4 v[34:49], v[74:81], v[34:41], 0, v198, v198 op_sel_hi:[0,0,0]
	v_mov_b32_e32 v59, v187
	v_cvt_pk_fp8_f32 v59, v154, v155
	v_bfe_u32 v60, v204, 3, 3
	v_mov_b32_e32 v61, s4
	v_mad_u32_u24 v209, v60, s95, v61
	v_cvt_pk_fp8_f32 v59, v156, v157 op_sel:[0,0,1]
	v_add_u32_e32 v60, s34, v209
	v_and_b32_e32 v210, 24, v206
	v_lshlrev_b32_e32 v211, 2, v58
	v_add3_u32 v58, v60, v210, v211
	ds_write_b32 v58, v59
	ds_read_b128 v[58:61], v131 offset:8320
	ds_read_b128 v[62:65], v131 offset:8336
	s_waitcnt lgkmcnt(4)
	v_mfma_scale_f32_32x32x64_f8f6f4 v[18:33], v[82:89], v[50:57], v[18:33], v198, v198 op_sel_hi:[0,0,0]
	v_add3_u32 v134, v208, s62, v207
	v_cvt_pk_bf16_f32 v132, v158, v159
	v_cvt_pk_bf16_f32 v133, v160, v161
	ds_write_b64 v134, v[132:133]
	v_mfma_scale_f32_32x32x64_f8f6f4 v[34:49], v[90:97], v[50:57], v[34:49], v198, v198 op_sel_hi:[0,0,0]
	v_mov_b32_e32 v50, v187
	v_cvt_pk_fp8_f32 v50, v158, v159
	v_add_u32_e32 v51, s63, v209
	v_add3_u32 v51, v51, v210, v211
	v_cvt_pk_fp8_f32 v50, v160, v161 op_sel:[0,0,1]
	ds_write_b32 v51, v50
	ds_read_b128 v[50:53], v131 offset:12480
	ds_read_b128 v[54:57], v131 offset:12496
	s_cbranch_scc1 .LBB0_1469
	global_load_dwordx4 v[154:157], v[194:195], off
	v_lshl_add_u64 v[132:133], v[194:195], 0, s[0:1]
	global_load_dwordx4 v[158:161], v[132:133], off
